# up-GEMM epilogue conv/SiLU on packed f32 ops (v_pk_fma/mul/add on column pairs): 785 instead of 1071 instructions
# speedup vs baseline: 1.0050x; 1.0050x over previous
; #define LAS __attribute__((address_space(3)))
;     __device__ __forceinline__ void operator()(f32x4 (&acc)[2][2][4][2], const Unit& u, int wr, int wc, int fr, int fq, const LAS float* rtab) const {
;         const int c0 = u.pn * 128 + wc * 32 + 8 * fq;
; #pragma unroll
;         for (int ai = 0; ai < 2; ++ai)
; #pragma unroll
;             for (int m = 0; m < 4; ++m) { const float r = rtab[ai * HALF + wr * 64 + m * 16 + fr];
; #pragma unroll
;                 for (int bj = 0; bj < 2; ++bj)
; #pragma unroll
;                     for (int n = 0; n < 2; ++n) acc[ai][bj][m][n] = acc[ai][bj][m][n] * r; }
;     ...
;             const f32x4 wg0 = *(const f32x4*)(cw + cn), wg1 = *(const f32x4*)(cw + UP_N + cn), wg2 = *(const f32x4*)(cw + 2 * UP_N + cn), bg = *(const f32x4*)(cb + cn);
;             const f32x4 wu0 = *(const f32x4*)(cw + DFF + cn), wu1 = *(const f32x4*)(cw + UP_N + DFF + cn), wu2 = *(const f32x4*)(cw + 2 * UP_N + DFF + cn), bu = *(const f32x4*)(cb + DFF + cn);
.LBB0_839:
	v_lshl_add_u32 v252, s1, 10, v192
	v_mad_u32_u24 v252, v134, 12, v252
	ds_read_b128 v[228:231], v252
	ds_read_b128 v[232:235], v252 offset:512
	v_lshl_or_b32 v213, s0, 7, v193
	v_lshlrev_b32_e32 v253, 2, v213
	global_load_dwordx4 v[144:147], v253, s[34:35]
	global_load_dwordx4 v[148:151], v253, s[34:35] offset:16
	global_load_dwordx4 v[152:155], v253, s[40:41]
	global_load_dwordx4 v[156:159], v253, s[40:41] offset:16
	global_load_dwordx4 v[160:163], v253, s[42:43]
	global_load_dwordx4 v[164:167], v253, s[42:43] offset:16
	global_load_dwordx4 v[168:171], v253, s[36:37]
	global_load_dwordx4 v[172:175], v253, s[36:37] offset:16
	global_load_dwordx4 v[180:183], v253, s[44:45]
	global_load_dwordx4 v[184:187], v253, s[44:45] offset:16
	global_load_dwordx4 v[188:191], v253, s[46:47]
	global_load_dwordx4 v[196:199], v253, s[46:47] offset:16
	global_load_dwordx4 v[200:203], v253, s[48:49]
	global_load_dwordx4 v[204:207], v253, s[48:49] offset:16
	global_load_dwordx4 v[220:223], v253, s[50:51]
	global_load_dwordx4 v[224:227], v253, s[50:51] offset:16
	s_waitcnt lgkmcnt(0)
	v_pk_mul_f32 v[124:125], v[124:125], v[228:229] op_sel_hi:[1,0]
	v_pk_mul_f32 v[126:127], v[126:127], v[228:229] op_sel_hi:[1,0]
	v_pk_mul_f32 v[120:121], v[120:121], v[228:229] op_sel_hi:[1,0]
	v_pk_mul_f32 v[122:123], v[122:123], v[228:229] op_sel_hi:[1,0]
	v_pk_mul_f32 v[116:117], v[116:117], v[228:229] op_sel_hi:[1,0]
	v_pk_mul_f32 v[118:119], v[118:119], v[228:229] op_sel_hi:[1,0]
	v_pk_mul_f32 v[112:113], v[112:113], v[228:229] op_sel_hi:[1,0]
	v_pk_mul_f32 v[114:115], v[114:115], v[228:229] op_sel_hi:[1,0]
	v_pk_mul_f32 v[68:69], v[68:69], v[228:229] op_sel:[0,1] op_sel_hi:[1,1]
	v_pk_mul_f32 v[70:71], v[70:71], v[228:229] op_sel:[0,1] op_sel_hi:[1,1]
	v_pk_mul_f32 v[64:65], v[64:65], v[228:229] op_sel:[0,1] op_sel_hi:[1,1]
	v_pk_mul_f32 v[66:67], v[66:67], v[228:229] op_sel:[0,1] op_sel_hi:[1,1]
	v_pk_mul_f32 v[52:53], v[52:53], v[228:229] op_sel:[0,1] op_sel_hi:[1,1]
	v_pk_mul_f32 v[54:55], v[54:55], v[228:229] op_sel:[0,1] op_sel_hi:[1,1]
	v_pk_mul_f32 v[48:49], v[48:49], v[228:229] op_sel:[0,1] op_sel_hi:[1,1]
	v_pk_mul_f32 v[50:51], v[50:51], v[228:229] op_sel:[0,1] op_sel_hi:[1,1]
	v_pk_mul_f32 v[60:61], v[60:61], v[230:231] op_sel_hi:[1,0]
	v_pk_mul_f32 v[62:63], v[62:63], v[230:231] op_sel_hi:[1,0]
	v_pk_mul_f32 v[20:21], v[20:21], v[230:231] op_sel_hi:[1,0]
	v_pk_mul_f32 v[22:23], v[22:23], v[230:231] op_sel_hi:[1,0]
	v_pk_mul_f32 v[44:45], v[44:45], v[230:231] op_sel_hi:[1,0]
	v_pk_mul_f32 v[46:47], v[46:47], v[230:231] op_sel_hi:[1,0]
	v_pk_mul_f32 v[16:17], v[16:17], v[230:231] op_sel_hi:[1,0]
	v_pk_mul_f32 v[18:19], v[18:19], v[230:231] op_sel_hi:[1,0]
	v_pk_mul_f32 v[108:109], v[108:109], v[230:231] op_sel:[0,1] op_sel_hi:[1,1]
	v_pk_mul_f32 v[110:111], v[110:111], v[230:231] op_sel:[0,1] op_sel_hi:[1,1]
	v_pk_mul_f32 v[104:105], v[104:105], v[230:231] op_sel:[0,1] op_sel_hi:[1,1]
	v_pk_mul_f32 v[106:107], v[106:107], v[230:231] op_sel:[0,1] op_sel_hi:[1,1]
	v_pk_mul_f32 v[100:101], v[100:101], v[230:231] op_sel:[0,1] op_sel_hi:[1,1]
	v_pk_mul_f32 v[102:103], v[102:103], v[230:231] op_sel:[0,1] op_sel_hi:[1,1]
	v_pk_mul_f32 v[96:97], v[96:97], v[230:231] op_sel:[0,1] op_sel_hi:[1,1]
	v_pk_mul_f32 v[98:99], v[98:99], v[230:231] op_sel:[0,1] op_sel_hi:[1,1]
	v_pk_mul_f32 v[92:93], v[92:93], v[232:233] op_sel_hi:[1,0]
	v_pk_mul_f32 v[94:95], v[94:95], v[232:233] op_sel_hi:[1,0]
	v_pk_mul_f32 v[88:89], v[88:89], v[232:233] op_sel_hi:[1,0]
	v_pk_mul_f32 v[90:91], v[90:91], v[232:233] op_sel_hi:[1,0]
	v_pk_mul_f32 v[84:85], v[84:85], v[232:233] op_sel_hi:[1,0]
	v_pk_mul_f32 v[86:87], v[86:87], v[232:233] op_sel_hi:[1,0]
	v_pk_mul_f32 v[80:81], v[80:81], v[232:233] op_sel_hi:[1,0]
	v_pk_mul_f32 v[82:83], v[82:83], v[232:233] op_sel_hi:[1,0]
	v_pk_mul_f32 v[36:37], v[36:37], v[232:233] op_sel:[0,1] op_sel_hi:[1,1]
	v_pk_mul_f32 v[38:39], v[38:39], v[232:233] op_sel:[0,1] op_sel_hi:[1,1]
	v_pk_mul_f32 v[12:13], v[12:13], v[232:233] op_sel:[0,1] op_sel_hi:[1,1]
	v_pk_mul_f32 v[14:15], v[14:15], v[232:233] op_sel:[0,1] op_sel_hi:[1,1]
	v_pk_mul_f32 v[28:29], v[28:29], v[232:233] op_sel:[0,1] op_sel_hi:[1,1]
	v_pk_mul_f32 v[30:31], v[30:31], v[232:233] op_sel:[0,1] op_sel_hi:[1,1]
	v_pk_mul_f32 v[8:9], v[8:9], v[232:233] op_sel:[0,1] op_sel_hi:[1,1]
	v_pk_mul_f32 v[10:11], v[10:11], v[232:233] op_sel:[0,1] op_sel_hi:[1,1]
	v_pk_mul_f32 v[32:33], v[32:33], v[234:235] op_sel_hi:[1,0]
	v_pk_mul_f32 v[34:35], v[34:35], v[234:235] op_sel_hi:[1,0]
	v_pk_mul_f32 v[4:5], v[4:5], v[234:235] op_sel_hi:[1,0]
	v_pk_mul_f32 v[6:7], v[6:7], v[234:235] op_sel_hi:[1,0]
	v_pk_mul_f32 v[24:25], v[24:25], v[234:235] op_sel_hi:[1,0]
	v_pk_mul_f32 v[26:27], v[26:27], v[234:235] op_sel_hi:[1,0]
	v_pk_mul_f32 v[0:1], v[0:1], v[234:235] op_sel_hi:[1,0]
	v_pk_mul_f32 v[2:3], v[2:3], v[234:235] op_sel_hi:[1,0]
	v_pk_mul_f32 v[76:77], v[76:77], v[234:235] op_sel:[0,1] op_sel_hi:[1,1]
	v_pk_mul_f32 v[78:79], v[78:79], v[234:235] op_sel:[0,1] op_sel_hi:[1,1]
	v_pk_mul_f32 v[56:57], v[56:57], v[234:235] op_sel:[0,1] op_sel_hi:[1,1]
	v_pk_mul_f32 v[58:59], v[58:59], v[234:235] op_sel:[0,1] op_sel_hi:[1,1]
	v_pk_mul_f32 v[72:73], v[72:73], v[234:235] op_sel:[0,1] op_sel_hi:[1,1]
	v_pk_mul_f32 v[74:75], v[74:75], v[234:235] op_sel:[0,1] op_sel_hi:[1,1]
	v_pk_mul_f32 v[40:41], v[40:41], v[234:235] op_sel:[0,1] op_sel_hi:[1,1]
	v_pk_mul_f32 v[42:43], v[42:43], v[234:235] op_sel:[0,1] op_sel_hi:[1,1]
	v_lshlrev_b32_e32 v235, 1, v213
	s_lshl_b32 s0, s18, 8
	s_add_i32 s0, s0, s69
	v_lshl_add_u32 v234, v134, 2, s0
	v_mul_lo_u32 v234, v234, s89
	v_add_u32_e32 v234, v234, v235
; __device__ __forceinline__ unsigned cvt_pk_bf16(float lo, float hi) { unsigned r; asm volatile("v_cvt_pk_bf16_f32 %0, %1, %2" : "=v"(r) : "v"(lo), "v"(hi)); return r; }
;     __device__ __forceinline__ void operator()(f32x4 (&acc)[2][2][4][2], const Unit& u, int wr, int wc, int fr, int fq, const LAS float* rtab) const {
;     ...
;         for (int ai = 0; ai < 2; ++ai) {
;             const int blk = (u.pm * BM + ai * HALF + wr * 64) >> 6;
;             if (fr < 2) { bf16_t* rp = raw + ((size_t)blk * 4 + fr) * UP_N + c0;
;                 const f32x4 g0 = acc[ai][0][0][0], g1 = acc[ai][0][0][1], u0 = acc[ai][1][0][0], u1 = acc[ai][1][0][1];
;                 u32x4 w; w.x = cvt_pk_bf16(g0[0], g0[1]); w.y = cvt_pk_bf16(g0[2], g0[3]); w.z = cvt_pk_bf16(g1[0], g1[1]); w.w = cvt_pk_bf16(g1[2], g1[3]); *(u32x4*)rp = w;
;                 w.x = cvt_pk_bf16(u0[0], u0[1]); w.y = cvt_pk_bf16(u0[2], u0[3]); w.z = cvt_pk_bf16(u1[0], u1[1]); w.w = cvt_pk_bf16(u1[2], u1[3]); *(u32x4*)(rp + DFF) = w; }
;             if (fr >= 14) { bf16_t* rp = raw + ((size_t)blk * 4 + (fr - 12)) * UP_N + c0;
;                 const f32x4 g0 = acc[ai][0][3][0], g1 = acc[ai][0][3][1], u0 = acc[ai][1][3][0], u1 = acc[ai][1][3][1];
;                 u32x4 w; w.x = cvt_pk_bf16(g0[0], g0[1]); w.y = cvt_pk_bf16(g0[2], g0[3]); w.z = cvt_pk_bf16(g1[0], g1[1]); w.w = cvt_pk_bf16(g1[2], g1[3]); *(u32x4*)rp = w;
;                 w.x = cvt_pk_bf16(u0[0], u0[1]); w.y = cvt_pk_bf16(u0[2], u0[3]); w.z = cvt_pk_bf16(u1[0], u1[1]); w.w = cvt_pk_bf16(u1[2], u1[3]); *(u32x4*)(rp + DFF) = w; }
;         }
	v_cmp_eq_u32_e64 s[54:55], 0, v134
	v_cmp_eq_u32_e64 s[56:57], 15, v134
	s_lshl_b32 s0, s18, 4
	s_lshr_b32 s1, s69, 4
	s_add_i32 s0, s0, s1
	s_add_i32 s1, s0, 0
	s_mul_i32 s1, s1, s88
	s_add_u32 s58, s30, s1
	s_addc_u32 s59, s31, 0
	s_mov_b64 exec, s[54:55]
	v_cvt_pk_bf16_f32 v244, v124, v125
	v_cvt_pk_bf16_f32 v245, v126, v127
	v_cvt_pk_bf16_f32 v246, v120, v121
	v_cvt_pk_bf16_f32 v247, v122, v123
	v_cvt_pk_bf16_f32 v248, v116, v117
	v_cvt_pk_bf16_f32 v249, v118, v119
	v_cvt_pk_bf16_f32 v250, v112, v113
	v_cvt_pk_bf16_f32 v251, v114, v115
	global_store_dwordx4 v235, v[244:247], s[58:59]
	s_add_u32 s58, s58, 0x2c00
	s_addc_u32 s59, s59, 0
	global_store_dwordx4 v235, v[248:251], s[58:59]
	s_add_i32 s1, s0, 1
	s_mul_i32 s1, s1, s88
	s_add_u32 s58, s30, s1
	s_addc_u32 s59, s31, 0
	s_mov_b64 exec, s[54:55]
	v_cvt_pk_bf16_f32 v236, v68, v69
	v_cvt_pk_bf16_f32 v237, v70, v71
	v_cvt_pk_bf16_f32 v238, v64, v65
	v_cvt_pk_bf16_f32 v239, v66, v67
	v_cvt_pk_bf16_f32 v240, v52, v53
	v_cvt_pk_bf16_f32 v241, v54, v55
	v_cvt_pk_bf16_f32 v242, v48, v49
	v_cvt_pk_bf16_f32 v243, v50, v51
	global_store_dwordx4 v235, v[236:239], s[58:59]
	s_add_u32 s58, s58, 0x2c00
	s_addc_u32 s59, s59, 0
	global_store_dwordx4 v235, v[240:243], s[58:59]
	s_add_i32 s1, s0, 2
	s_mul_i32 s1, s1, s88
	s_add_u32 s58, s30, s1
	s_addc_u32 s59, s31, 0
	s_mov_b64 exec, s[56:57]
	v_cvt_pk_bf16_f32 v244, v60, v61
	v_cvt_pk_bf16_f32 v245, v62, v63
	v_cvt_pk_bf16_f32 v246, v20, v21
	v_cvt_pk_bf16_f32 v247, v22, v23
	v_cvt_pk_bf16_f32 v248, v44, v45
	v_cvt_pk_bf16_f32 v249, v46, v47
	v_cvt_pk_bf16_f32 v250, v16, v17
	v_cvt_pk_bf16_f32 v251, v18, v19
	global_store_dwordx4 v235, v[244:247], s[58:59]
	s_add_u32 s58, s58, 0x2c00
	s_addc_u32 s59, s59, 0
	global_store_dwordx4 v235, v[248:251], s[58:59]
	s_add_i32 s1, s0, 3
	s_mul_i32 s1, s1, s88
	s_add_u32 s58, s30, s1
	s_addc_u32 s59, s31, 0
	s_mov_b64 exec, s[56:57]
	v_cvt_pk_bf16_f32 v236, v108, v109
	v_cvt_pk_bf16_f32 v237, v110, v111
	v_cvt_pk_bf16_f32 v238, v104, v105
	v_cvt_pk_bf16_f32 v239, v106, v107
	v_cvt_pk_bf16_f32 v240, v100, v101
	v_cvt_pk_bf16_f32 v241, v102, v103
	v_cvt_pk_bf16_f32 v242, v96, v97
	v_cvt_pk_bf16_f32 v243, v98, v99
	global_store_dwordx4 v235, v[236:239], s[58:59]
	s_add_u32 s58, s58, 0x2c00
	s_addc_u32 s59, s59, 0
	global_store_dwordx4 v235, v[240:243], s[58:59]
	s_add_i32 s1, s0, 8
	s_mul_i32 s1, s1, s88
	s_add_u32 s58, s30, s1
	s_addc_u32 s59, s31, 0
	s_mov_b64 exec, s[54:55]
	v_cvt_pk_bf16_f32 v244, v92, v93
	v_cvt_pk_bf16_f32 v245, v94, v95
	v_cvt_pk_bf16_f32 v246, v88, v89
	v_cvt_pk_bf16_f32 v247, v90, v91
	v_cvt_pk_bf16_f32 v248, v84, v85
	v_cvt_pk_bf16_f32 v249, v86, v87
	v_cvt_pk_bf16_f32 v250, v80, v81
	v_cvt_pk_bf16_f32 v251, v82, v83
	global_store_dwordx4 v235, v[244:247], s[58:59]
	s_add_u32 s58, s58, 0x2c00
	s_addc_u32 s59, s59, 0
	global_store_dwordx4 v235, v[248:251], s[58:59]
	s_add_i32 s1, s0, 9
	s_mul_i32 s1, s1, s88
	s_add_u32 s58, s30, s1
	s_addc_u32 s59, s31, 0
	s_mov_b64 exec, s[54:55]
	v_cvt_pk_bf16_f32 v236, v36, v37
	v_cvt_pk_bf16_f32 v237, v38, v39
	v_cvt_pk_bf16_f32 v238, v12, v13
	v_cvt_pk_bf16_f32 v239, v14, v15
	v_cvt_pk_bf16_f32 v240, v28, v29
	v_cvt_pk_bf16_f32 v241, v30, v31
	v_cvt_pk_bf16_f32 v242, v8, v9
	v_cvt_pk_bf16_f32 v243, v10, v11
	global_store_dwordx4 v235, v[236:239], s[58:59]
	s_add_u32 s58, s58, 0x2c00
	s_addc_u32 s59, s59, 0
	global_store_dwordx4 v235, v[240:243], s[58:59]
	s_add_i32 s1, s0, 10
	s_mul_i32 s1, s1, s88
	s_add_u32 s58, s30, s1
	s_addc_u32 s59, s31, 0
	s_mov_b64 exec, s[56:57]
	v_cvt_pk_bf16_f32 v244, v32, v33
	v_cvt_pk_bf16_f32 v245, v34, v35
	v_cvt_pk_bf16_f32 v246, v4, v5
	v_cvt_pk_bf16_f32 v247, v6, v7
	v_cvt_pk_bf16_f32 v248, v24, v25
	v_cvt_pk_bf16_f32 v249, v26, v27
	v_cvt_pk_bf16_f32 v250, v0, v1
	v_cvt_pk_bf16_f32 v251, v2, v3
	global_store_dwordx4 v235, v[244:247], s[58:59]
	s_add_u32 s58, s58, 0x2c00
	s_addc_u32 s59, s59, 0
	global_store_dwordx4 v235, v[248:251], s[58:59]
	s_add_i32 s1, s0, 11
	s_mul_i32 s1, s1, s88
	s_add_u32 s58, s30, s1
	s_addc_u32 s59, s31, 0
	s_mov_b64 exec, s[56:57]
	v_cvt_pk_bf16_f32 v236, v76, v77
	v_cvt_pk_bf16_f32 v237, v78, v79
	v_cvt_pk_bf16_f32 v238, v56, v57
	v_cvt_pk_bf16_f32 v239, v58, v59
	v_cvt_pk_bf16_f32 v240, v72, v73
	v_cvt_pk_bf16_f32 v241, v74, v75
	v_cvt_pk_bf16_f32 v242, v40, v41
	v_cvt_pk_bf16_f32 v243, v42, v43
	global_store_dwordx4 v235, v[236:239], s[58:59]
	s_add_u32 s58, s58, 0x2c00
	s_addc_u32 s59, s59, 0
	global_store_dwordx4 v235, v[240:243], s[58:59]
	s_mov_b64 exec, -1
	s_waitcnt vmcnt(16)
; __device__ __forceinline__ unsigned cvt_pk_bf16(float lo, float hi) { unsigned r; asm volatile("v_cvt_pk_bf16_f32 %0, %1, %2" : "=v"(r) : "v"(lo), "v"(hi)); return r; }
; template <int CTRL> __device__ __forceinline__ float dppz(float v) { return __int_as_float(__builtin_amdgcn_update_dpp(0, __float_as_int(v), CTRL, 0xf, 0xf, true)); }
;     __device__ __forceinline__ void operator()(f32x4 (&acc)[2][2][4][2], const Unit& u, int wr, int wc, int fr, int fq, const LAS float* rtab) const {
;     ...
;                         const float gc = acc[ai][0][m][n][jj], uc = acc[ai][1][m][n][jj];
;                         const float gb = m > 0 ? acc[ai][0][m - 1][n][jj] : 0.f, ga = m < 3 ? acc[ai][0][m + 1][n][jj] : 0.f;
;                         const float ub = m > 0 ? acc[ai][1][m - 1][n][jj] : 0.f, ua = m < 3 ? acc[ai][1][m + 1][n][jj] : 0.f;
;                         const float gp = dppz<0x111>(gc) + dppz<0x10F>(gb), gn = dppz<0x101>(gc) + dppz<0x11F>(ga);
;                         const float up = dppz<0x111>(uc) + dppz<0x10F>(ub), un = dppz<0x101>(uc) + dppz<0x11F>(ua);
;                         const float hg = wg0[jj] * gp + wg1[jj] * gc + wg2[jj] * gn + bg[jj];
;                         const float hu = wu0[jj] * up + wu1[jj] * uc + wu2[jj] * un + bu[jj];
;                         const float sg = __builtin_amdgcn_rcpf(1.f + __builtin_amdgcn_exp2f(-1.4426950408889634f * hg));
;                         y[jj] = hg * sg * hu; }
;                     u32x2 pk; pk.x = cvt_pk_bf16(y[0], y[1]); pk.y = cvt_pk_bf16(y[2], y[3]);
	s_mov_b32 s54, 0xbfb8aa3b
	s_mov_b32 s56, 1.0
	v_pk_fma_f32 v[142:143], v[152:153], v[124:125], v[168:169]
	v_pk_fma_f32 v[178:179], v[152:153], v[68:69], v[168:169]
	v_pk_fma_f32 v[210:211], v[152:153], v[60:61], v[168:169]
	v_pk_fma_f32 v[212:213], v[152:153], v[108:109], v[168:169]
	v_pk_fma_f32 v[142:143], v[160:161], v[68:69], v[142:143]
	v_pk_fma_f32 v[178:179], v[144:145], v[124:125], v[178:179]
	v_pk_fma_f32 v[210:211], v[144:145], v[68:69], v[210:211]
	v_pk_fma_f32 v[212:213], v[144:145], v[60:61], v[212:213]
	v_pk_fma_f32 v[178:179], v[160:161], v[60:61], v[178:179]
	v_pk_fma_f32 v[210:211], v[160:161], v[108:109], v[210:211]
	v_fmac_f32_dpp v142, v108, v144 row_shr:1 row_mask:0xf bank_mask:0xf bound_ctrl:1
	v_fmac_f32_dpp v212, v124, v160 row_shl:1 row_mask:0xf bank_mask:0xf bound_ctrl:1
	v_fmac_f32_dpp v143, v109, v145 row_shr:1 row_mask:0xf bank_mask:0xf bound_ctrl:1
	v_fmac_f32_dpp v213, v125, v161 row_shl:1 row_mask:0xf bank_mask:0xf bound_ctrl:1
	v_pk_mul_f32 v[218:219], v[142:143], s[54:55] op_sel_hi:[1,0]
	v_pk_mul_f32 v[252:253], v[178:179], s[54:55] op_sel_hi:[1,0]
	v_pk_mul_f32 v[228:229], v[210:211], s[54:55] op_sel_hi:[1,0]
	v_pk_mul_f32 v[230:231], v[212:213], s[54:55] op_sel_hi:[1,0]
	v_exp_f32_e32 v218, v218
	v_exp_f32_e32 v219, v219
	v_exp_f32_e32 v252, v252
	v_exp_f32_e32 v253, v253
	v_exp_f32_e32 v228, v228
	v_exp_f32_e32 v229, v229
	v_exp_f32_e32 v230, v230
	v_exp_f32_e32 v231, v231
	v_pk_add_f32 v[218:219], v[218:219], s[56:57] op_sel_hi:[1,0]
	v_pk_add_f32 v[252:253], v[252:253], s[56:57] op_sel_hi:[1,0]
	v_pk_add_f32 v[228:229], v[228:229], s[56:57] op_sel_hi:[1,0]
	v_pk_add_f32 v[230:231], v[230:231], s[56:57] op_sel_hi:[1,0]
	v_rcp_f32_e32 v218, v218
	v_rcp_f32_e32 v219, v219
	v_rcp_f32_e32 v252, v252
	v_rcp_f32_e32 v253, v253
	v_rcp_f32_e32 v228, v228
	v_rcp_f32_e32 v229, v229
	v_rcp_f32_e32 v230, v230
	v_rcp_f32_e32 v231, v231
	v_pk_mul_f32 v[142:143], v[142:143], v[218:219]
	v_pk_mul_f32 v[178:179], v[178:179], v[252:253]
	v_pk_mul_f32 v[210:211], v[210:211], v[228:229]
	v_pk_mul_f32 v[212:213], v[212:213], v[230:231]
	v_pk_fma_f32 v[218:219], v[188:189], v[116:117], v[220:221]
	v_pk_fma_f32 v[252:253], v[188:189], v[52:53], v[220:221]
	v_pk_fma_f32 v[228:229], v[188:189], v[44:45], v[220:221]
	v_pk_fma_f32 v[230:231], v[188:189], v[100:101], v[220:221]
	v_pk_fma_f32 v[218:219], v[200:201], v[52:53], v[218:219]
	v_pk_fma_f32 v[252:253], v[180:181], v[116:117], v[252:253]
	v_pk_fma_f32 v[228:229], v[180:181], v[52:53], v[228:229]
	v_pk_fma_f32 v[230:231], v[180:181], v[44:45], v[230:231]
	v_pk_fma_f32 v[252:253], v[200:201], v[44:45], v[252:253]
	v_pk_fma_f32 v[228:229], v[200:201], v[100:101], v[228:229]
	v_fmac_f32_dpp v218, v100, v180 row_shr:1 row_mask:0xf bank_mask:0xf bound_ctrl:1
	v_fmac_f32_dpp v230, v116, v200 row_shl:1 row_mask:0xf bank_mask:0xf bound_ctrl:1
	v_fmac_f32_dpp v219, v101, v181 row_shr:1 row_mask:0xf bank_mask:0xf bound_ctrl:1
	v_fmac_f32_dpp v231, v117, v201 row_shl:1 row_mask:0xf bank_mask:0xf bound_ctrl:1
	v_pk_mul_f32 v[142:143], v[142:143], v[218:219]
	v_pk_mul_f32 v[178:179], v[178:179], v[252:253]
	v_pk_mul_f32 v[210:211], v[210:211], v[228:229]
	v_pk_mul_f32 v[212:213], v[212:213], v[230:231]
	v_cvt_pk_bf16_f32 v236, v142, v143
	v_cvt_pk_bf16_f32 v240, v178, v179
	v_cvt_pk_bf16_f32 v244, v210, v211
	v_cvt_pk_bf16_f32 v248, v212, v213
	v_pk_fma_f32 v[142:143], v[154:155], v[126:127], v[170:171]
	v_pk_fma_f32 v[178:179], v[154:155], v[70:71], v[170:171]
	v_pk_fma_f32 v[210:211], v[154:155], v[62:63], v[170:171]
	v_pk_fma_f32 v[212:213], v[154:155], v[110:111], v[170:171]
	v_pk_fma_f32 v[142:143], v[162:163], v[70:71], v[142:143]
	v_pk_fma_f32 v[178:179], v[146:147], v[126:127], v[178:179]
	v_pk_fma_f32 v[210:211], v[146:147], v[70:71], v[210:211]
	v_pk_fma_f32 v[212:213], v[146:147], v[62:63], v[212:213]
	v_pk_fma_f32 v[178:179], v[162:163], v[62:63], v[178:179]
	v_pk_fma_f32 v[210:211], v[162:163], v[110:111], v[210:211]
	v_fmac_f32_dpp v142, v110, v146 row_shr:1 row_mask:0xf bank_mask:0xf bound_ctrl:1
	v_fmac_f32_dpp v212, v126, v162 row_shl:1 row_mask:0xf bank_mask:0xf bound_ctrl:1
	v_fmac_f32_dpp v143, v111, v147 row_shr:1 row_mask:0xf bank_mask:0xf bound_ctrl:1
	v_fmac_f32_dpp v213, v127, v163 row_shl:1 row_mask:0xf bank_mask:0xf bound_ctrl:1
	v_pk_mul_f32 v[218:219], v[142:143], s[54:55] op_sel_hi:[1,0]
	v_pk_mul_f32 v[252:253], v[178:179], s[54:55] op_sel_hi:[1,0]
	v_pk_mul_f32 v[228:229], v[210:211], s[54:55] op_sel_hi:[1,0]
	v_pk_mul_f32 v[230:231], v[212:213], s[54:55] op_sel_hi:[1,0]
	v_exp_f32_e32 v218, v218
	v_exp_f32_e32 v219, v219
	v_exp_f32_e32 v252, v252
	v_exp_f32_e32 v253, v253
	v_exp_f32_e32 v228, v228
	v_exp_f32_e32 v229, v229
	v_exp_f32_e32 v230, v230
	v_exp_f32_e32 v231, v231
	v_pk_add_f32 v[218:219], v[218:219], s[56:57] op_sel_hi:[1,0]
	v_pk_add_f32 v[252:253], v[252:253], s[56:57] op_sel_hi:[1,0]
	v_pk_add_f32 v[228:229], v[228:229], s[56:57] op_sel_hi:[1,0]
	v_pk_add_f32 v[230:231], v[230:231], s[56:57] op_sel_hi:[1,0]
	v_rcp_f32_e32 v218, v218
	v_rcp_f32_e32 v219, v219
	v_rcp_f32_e32 v252, v252
	v_rcp_f32_e32 v253, v253
	v_rcp_f32_e32 v228, v228
	v_rcp_f32_e32 v229, v229
	v_rcp_f32_e32 v230, v230
	v_rcp_f32_e32 v231, v231
	v_pk_mul_f32 v[142:143], v[142:143], v[218:219]
	v_pk_mul_f32 v[178:179], v[178:179], v[252:253]
	v_pk_mul_f32 v[210:211], v[210:211], v[228:229]
	v_pk_mul_f32 v[212:213], v[212:213], v[230:231]
	v_pk_fma_f32 v[218:219], v[190:191], v[118:119], v[222:223]
	v_pk_fma_f32 v[252:253], v[190:191], v[54:55], v[222:223]
	v_pk_fma_f32 v[228:229], v[190:191], v[46:47], v[222:223]
	v_pk_fma_f32 v[230:231], v[190:191], v[102:103], v[222:223]
; __device__ __forceinline__ unsigned cvt_pk_bf16(float lo, float hi) { unsigned r; asm volatile("v_cvt_pk_bf16_f32 %0, %1, %2" : "=v"(r) : "v"(lo), "v"(hi)); return r; }
; template <int CTRL> __device__ __forceinline__ float dppz(float v) { return __int_as_float(__builtin_amdgcn_update_dpp(0, __float_as_int(v), CTRL, 0xf, 0xf, true)); }
;     __device__ __forceinline__ void operator()(f32x4 (&acc)[2][2][4][2], const Unit& u, int wr, int wc, int fr, int fq, const LAS float* rtab) const {
;     ...
;                         const float gc = acc[ai][0][m][n][jj], uc = acc[ai][1][m][n][jj];
;                         const float gb = m > 0 ? acc[ai][0][m - 1][n][jj] : 0.f, ga = m < 3 ? acc[ai][0][m + 1][n][jj] : 0.f;
;                         const float ub = m > 0 ? acc[ai][1][m - 1][n][jj] : 0.f, ua = m < 3 ? acc[ai][1][m + 1][n][jj] : 0.f;
;                         const float gp = dppz<0x111>(gc) + dppz<0x10F>(gb), gn = dppz<0x101>(gc) + dppz<0x11F>(ga);
;                         const float up = dppz<0x111>(uc) + dppz<0x10F>(ub), un = dppz<0x101>(uc) + dppz<0x11F>(ua);
;                         const float hg = wg0[jj] * gp + wg1[jj] * gc + wg2[jj] * gn + bg[jj];
;                         const float hu = wu0[jj] * up + wu1[jj] * uc + wu2[jj] * un + bu[jj];
;                         const float sg = __builtin_amdgcn_rcpf(1.f + __builtin_amdgcn_exp2f(-1.4426950408889634f * hg));
;                         y[jj] = hg * sg * hu; }
;                     u32x2 pk; pk.x = cvt_pk_bf16(y[0], y[1]); pk.y = cvt_pk_bf16(y[2], y[3]);
	v_pk_fma_f32 v[218:219], v[202:203], v[54:55], v[218:219]
	v_pk_fma_f32 v[252:253], v[182:183], v[118:119], v[252:253]
	v_pk_fma_f32 v[228:229], v[182:183], v[54:55], v[228:229]
	v_pk_fma_f32 v[230:231], v[182:183], v[46:47], v[230:231]
	v_pk_fma_f32 v[252:253], v[202:203], v[46:47], v[252:253]
	v_pk_fma_f32 v[228:229], v[202:203], v[102:103], v[228:229]
	v_fmac_f32_dpp v218, v102, v182 row_shr:1 row_mask:0xf bank_mask:0xf bound_ctrl:1
	v_fmac_f32_dpp v230, v118, v202 row_shl:1 row_mask:0xf bank_mask:0xf bound_ctrl:1
	v_fmac_f32_dpp v219, v103, v183 row_shr:1 row_mask:0xf bank_mask:0xf bound_ctrl:1
	v_fmac_f32_dpp v231, v119, v203 row_shl:1 row_mask:0xf bank_mask:0xf bound_ctrl:1
	v_pk_mul_f32 v[142:143], v[142:143], v[218:219]
	v_pk_mul_f32 v[178:179], v[178:179], v[252:253]
	v_pk_mul_f32 v[210:211], v[210:211], v[228:229]
	v_pk_mul_f32 v[212:213], v[212:213], v[230:231]
	v_cvt_pk_bf16_f32 v237, v142, v143
	v_cvt_pk_bf16_f32 v241, v178, v179
	v_cvt_pk_bf16_f32 v245, v210, v211
	v_cvt_pk_bf16_f32 v249, v212, v213
	v_pk_fma_f32 v[142:143], v[156:157], v[120:121], v[172:173]
	v_pk_fma_f32 v[178:179], v[156:157], v[64:65], v[172:173]
	v_pk_fma_f32 v[210:211], v[156:157], v[20:21], v[172:173]
	v_pk_fma_f32 v[212:213], v[156:157], v[104:105], v[172:173]
	v_pk_fma_f32 v[142:143], v[164:165], v[64:65], v[142:143]
	v_pk_fma_f32 v[178:179], v[148:149], v[120:121], v[178:179]
	v_pk_fma_f32 v[210:211], v[148:149], v[64:65], v[210:211]
	v_pk_fma_f32 v[212:213], v[148:149], v[20:21], v[212:213]
	v_pk_fma_f32 v[178:179], v[164:165], v[20:21], v[178:179]
	v_pk_fma_f32 v[210:211], v[164:165], v[104:105], v[210:211]
	v_fmac_f32_dpp v142, v104, v148 row_shr:1 row_mask:0xf bank_mask:0xf bound_ctrl:1
	v_fmac_f32_dpp v212, v120, v164 row_shl:1 row_mask:0xf bank_mask:0xf bound_ctrl:1
	v_fmac_f32_dpp v143, v105, v149 row_shr:1 row_mask:0xf bank_mask:0xf bound_ctrl:1
	v_fmac_f32_dpp v213, v121, v165 row_shl:1 row_mask:0xf bank_mask:0xf bound_ctrl:1
	v_pk_mul_f32 v[218:219], v[142:143], s[54:55] op_sel_hi:[1,0]
	v_pk_mul_f32 v[252:253], v[178:179], s[54:55] op_sel_hi:[1,0]
	v_pk_mul_f32 v[228:229], v[210:211], s[54:55] op_sel_hi:[1,0]
	v_pk_mul_f32 v[230:231], v[212:213], s[54:55] op_sel_hi:[1,0]
	v_exp_f32_e32 v218, v218
	v_exp_f32_e32 v219, v219
	v_exp_f32_e32 v252, v252
	v_exp_f32_e32 v253, v253
	v_exp_f32_e32 v228, v228
	v_exp_f32_e32 v229, v229
	v_exp_f32_e32 v230, v230
	v_exp_f32_e32 v231, v231
	v_pk_add_f32 v[218:219], v[218:219], s[56:57] op_sel_hi:[1,0]
	v_pk_add_f32 v[252:253], v[252:253], s[56:57] op_sel_hi:[1,0]
	v_pk_add_f32 v[228:229], v[228:229], s[56:57] op_sel_hi:[1,0]
	v_pk_add_f32 v[230:231], v[230:231], s[56:57] op_sel_hi:[1,0]
	v_rcp_f32_e32 v218, v218
	v_rcp_f32_e32 v219, v219
	v_rcp_f32_e32 v252, v252
	v_rcp_f32_e32 v253, v253
	v_rcp_f32_e32 v228, v228
	v_rcp_f32_e32 v229, v229
	v_rcp_f32_e32 v230, v230
	v_rcp_f32_e32 v231, v231
	v_pk_mul_f32 v[142:143], v[142:143], v[218:219]
	v_pk_mul_f32 v[178:179], v[178:179], v[252:253]
	v_pk_mul_f32 v[210:211], v[210:211], v[228:229]
	v_pk_mul_f32 v[212:213], v[212:213], v[230:231]
	v_pk_fma_f32 v[218:219], v[196:197], v[112:113], v[224:225]
	v_pk_fma_f32 v[252:253], v[196:197], v[48:49], v[224:225]
	v_pk_fma_f32 v[228:229], v[196:197], v[16:17], v[224:225]
	v_pk_fma_f32 v[230:231], v[196:197], v[96:97], v[224:225]
	v_pk_fma_f32 v[218:219], v[204:205], v[48:49], v[218:219]
	v_pk_fma_f32 v[252:253], v[184:185], v[112:113], v[252:253]
	v_pk_fma_f32 v[228:229], v[184:185], v[48:49], v[228:229]
	v_pk_fma_f32 v[230:231], v[184:185], v[16:17], v[230:231]
	v_pk_fma_f32 v[252:253], v[204:205], v[16:17], v[252:253]
	v_pk_fma_f32 v[228:229], v[204:205], v[96:97], v[228:229]
	v_fmac_f32_dpp v218, v96, v184 row_shr:1 row_mask:0xf bank_mask:0xf bound_ctrl:1
	v_fmac_f32_dpp v230, v112, v204 row_shl:1 row_mask:0xf bank_mask:0xf bound_ctrl:1
	v_fmac_f32_dpp v219, v97, v185 row_shr:1 row_mask:0xf bank_mask:0xf bound_ctrl:1
	v_fmac_f32_dpp v231, v113, v205 row_shl:1 row_mask:0xf bank_mask:0xf bound_ctrl:1
	v_pk_mul_f32 v[142:143], v[142:143], v[218:219]
	v_pk_mul_f32 v[178:179], v[178:179], v[252:253]
	v_pk_mul_f32 v[210:211], v[210:211], v[228:229]
	v_pk_mul_f32 v[212:213], v[212:213], v[230:231]
	v_cvt_pk_bf16_f32 v238, v142, v143
	v_cvt_pk_bf16_f32 v242, v178, v179
	v_cvt_pk_bf16_f32 v246, v210, v211
	v_cvt_pk_bf16_f32 v250, v212, v213
	v_pk_fma_f32 v[142:143], v[158:159], v[122:123], v[174:175]
	v_pk_fma_f32 v[178:179], v[158:159], v[66:67], v[174:175]
	v_pk_fma_f32 v[210:211], v[158:159], v[22:23], v[174:175]
	v_pk_fma_f32 v[212:213], v[158:159], v[106:107], v[174:175]
	v_pk_fma_f32 v[142:143], v[166:167], v[66:67], v[142:143]
	v_pk_fma_f32 v[178:179], v[150:151], v[122:123], v[178:179]
	v_pk_fma_f32 v[210:211], v[150:151], v[66:67], v[210:211]
	v_pk_fma_f32 v[212:213], v[150:151], v[22:23], v[212:213]
	v_pk_fma_f32 v[178:179], v[166:167], v[22:23], v[178:179]
	v_pk_fma_f32 v[210:211], v[166:167], v[106:107], v[210:211]
	v_fmac_f32_dpp v142, v106, v150 row_shr:1 row_mask:0xf bank_mask:0xf bound_ctrl:1
	v_fmac_f32_dpp v212, v122, v166 row_shl:1 row_mask:0xf bank_mask:0xf bound_ctrl:1
	v_fmac_f32_dpp v143, v107, v151 row_shr:1 row_mask:0xf bank_mask:0xf bound_ctrl:1
	v_fmac_f32_dpp v213, v123, v167 row_shl:1 row_mask:0xf bank_mask:0xf bound_ctrl:1
	v_pk_mul_f32 v[218:219], v[142:143], s[54:55] op_sel_hi:[1,0]
	v_pk_mul_f32 v[252:253], v[178:179], s[54:55] op_sel_hi:[1,0]
	v_pk_mul_f32 v[228:229], v[210:211], s[54:55] op_sel_hi:[1,0]
	v_pk_mul_f32 v[230:231], v[212:213], s[54:55] op_sel_hi:[1,0]
	v_exp_f32_e32 v218, v218
	v_exp_f32_e32 v219, v219
	v_exp_f32_e32 v252, v252
	v_exp_f32_e32 v253, v253
	v_exp_f32_e32 v228, v228
; __device__ __forceinline__ unsigned cvt_pk_bf16(float lo, float hi) { unsigned r; asm volatile("v_cvt_pk_bf16_f32 %0, %1, %2" : "=v"(r) : "v"(lo), "v"(hi)); return r; }
; template <int CTRL> __device__ __forceinline__ float dppz(float v) { return __int_as_float(__builtin_amdgcn_update_dpp(0, __float_as_int(v), CTRL, 0xf, 0xf, true)); }
;     __device__ __forceinline__ void operator()(f32x4 (&acc)[2][2][4][2], const Unit& u, int wr, int wc, int fr, int fq, const LAS float* rtab) const {
;     ...
;                         const float gc = acc[ai][0][m][n][jj], uc = acc[ai][1][m][n][jj];
;                         const float gb = m > 0 ? acc[ai][0][m - 1][n][jj] : 0.f, ga = m < 3 ? acc[ai][0][m + 1][n][jj] : 0.f;
;                         const float ub = m > 0 ? acc[ai][1][m - 1][n][jj] : 0.f, ua = m < 3 ? acc[ai][1][m + 1][n][jj] : 0.f;
;                         const float gp = dppz<0x111>(gc) + dppz<0x10F>(gb), gn = dppz<0x101>(gc) + dppz<0x11F>(ga);
;                         const float up = dppz<0x111>(uc) + dppz<0x10F>(ub), un = dppz<0x101>(uc) + dppz<0x11F>(ua);
;                         const float hg = wg0[jj] * gp + wg1[jj] * gc + wg2[jj] * gn + bg[jj];
;                         const float hu = wu0[jj] * up + wu1[jj] * uc + wu2[jj] * un + bu[jj];
;                         const float sg = __builtin_amdgcn_rcpf(1.f + __builtin_amdgcn_exp2f(-1.4426950408889634f * hg));
;                         y[jj] = hg * sg * hu; }
;                     u32x2 pk; pk.x = cvt_pk_bf16(y[0], y[1]); pk.y = cvt_pk_bf16(y[2], y[3]);
;                     if (n == 0) ypk[ai][m] = pk;
;                     else {
;                         const bool deferred = (m == 0 && fr == 0) || (m == 3 && fr == 15);
;                         if (!deferred) { u32x4 w; w.x = ypk[ai][m].x; w.y = ypk[ai][m].y; w.z = pk.x; w.w = pk.y; *(u32x4*)(act + (size_t)(r64 + m * 16 + fr) * DFF + c0) = w; } }
	v_exp_f32_e32 v229, v229
	v_exp_f32_e32 v230, v230
	v_exp_f32_e32 v231, v231
	v_pk_add_f32 v[218:219], v[218:219], s[56:57] op_sel_hi:[1,0]
	v_pk_add_f32 v[252:253], v[252:253], s[56:57] op_sel_hi:[1,0]
	v_pk_add_f32 v[228:229], v[228:229], s[56:57] op_sel_hi:[1,0]
	v_pk_add_f32 v[230:231], v[230:231], s[56:57] op_sel_hi:[1,0]
	v_rcp_f32_e32 v218, v218
	v_rcp_f32_e32 v219, v219
	v_rcp_f32_e32 v252, v252
	v_rcp_f32_e32 v253, v253
	v_rcp_f32_e32 v228, v228
	v_rcp_f32_e32 v229, v229
	v_rcp_f32_e32 v230, v230
	v_rcp_f32_e32 v231, v231
	v_pk_mul_f32 v[142:143], v[142:143], v[218:219]
	v_pk_mul_f32 v[178:179], v[178:179], v[252:253]
	v_pk_mul_f32 v[210:211], v[210:211], v[228:229]
	v_pk_mul_f32 v[212:213], v[212:213], v[230:231]
	v_pk_fma_f32 v[218:219], v[198:199], v[114:115], v[226:227]
	v_pk_fma_f32 v[252:253], v[198:199], v[50:51], v[226:227]
	v_pk_fma_f32 v[228:229], v[198:199], v[18:19], v[226:227]
	v_pk_fma_f32 v[230:231], v[198:199], v[98:99], v[226:227]
	v_pk_fma_f32 v[218:219], v[206:207], v[50:51], v[218:219]
	v_pk_fma_f32 v[252:253], v[186:187], v[114:115], v[252:253]
	v_pk_fma_f32 v[228:229], v[186:187], v[50:51], v[228:229]
	v_pk_fma_f32 v[230:231], v[186:187], v[18:19], v[230:231]
	v_pk_fma_f32 v[252:253], v[206:207], v[18:19], v[252:253]
	v_pk_fma_f32 v[228:229], v[206:207], v[98:99], v[228:229]
	v_fmac_f32_dpp v218, v98, v186 row_shr:1 row_mask:0xf bank_mask:0xf bound_ctrl:1
	v_fmac_f32_dpp v230, v114, v206 row_shl:1 row_mask:0xf bank_mask:0xf bound_ctrl:1
	v_fmac_f32_dpp v219, v99, v187 row_shr:1 row_mask:0xf bank_mask:0xf bound_ctrl:1
	v_fmac_f32_dpp v231, v115, v207 row_shl:1 row_mask:0xf bank_mask:0xf bound_ctrl:1
	v_pk_mul_f32 v[142:143], v[142:143], v[218:219]
	v_pk_mul_f32 v[178:179], v[178:179], v[252:253]
	v_pk_mul_f32 v[210:211], v[210:211], v[228:229]
	v_pk_mul_f32 v[212:213], v[212:213], v[230:231]
	v_cvt_pk_bf16_f32 v239, v142, v143
	v_cvt_pk_bf16_f32 v243, v178, v179
	v_cvt_pk_bf16_f32 v247, v210, v211
	v_cvt_pk_bf16_f32 v251, v212, v213
	s_mov_b64 s[58:59], s[28:29]
	s_mov_b64 exec, s[12:13]
	global_store_dwordx4 v234, v[236:239], s[58:59]
	s_mov_b64 exec, -1
	s_add_u32 s58, s28, 0x2c00
	s_addc_u32 s59, s29, 0
	global_store_dwordx4 v234, v[240:243], s[58:59]
	s_add_u32 s58, s28, 0x5800
	s_addc_u32 s59, s29, 0
	global_store_dwordx4 v234, v[244:247], s[58:59]
	s_add_u32 s58, s28, 0x8400
	s_addc_u32 s59, s29, 0
	s_mov_b64 exec, s[10:11]
	global_store_dwordx4 v234, v[248:251], s[58:59]
	s_mov_b64 exec, -1
	v_pk_fma_f32 v[142:143], v[152:153], v[92:93], v[168:169]
	v_pk_fma_f32 v[178:179], v[152:153], v[36:37], v[168:169]
	v_pk_fma_f32 v[210:211], v[152:153], v[32:33], v[168:169]
	v_pk_fma_f32 v[212:213], v[152:153], v[76:77], v[168:169]
	v_pk_fma_f32 v[142:143], v[160:161], v[36:37], v[142:143]
	v_pk_fma_f32 v[178:179], v[144:145], v[92:93], v[178:179]
	v_pk_fma_f32 v[210:211], v[144:145], v[36:37], v[210:211]
	v_pk_fma_f32 v[212:213], v[144:145], v[32:33], v[212:213]
	v_pk_fma_f32 v[178:179], v[160:161], v[32:33], v[178:179]
	v_pk_fma_f32 v[210:211], v[160:161], v[76:77], v[210:211]
	v_fmac_f32_dpp v142, v76, v144 row_shr:1 row_mask:0xf bank_mask:0xf bound_ctrl:1
	v_fmac_f32_dpp v212, v92, v160 row_shl:1 row_mask:0xf bank_mask:0xf bound_ctrl:1
	v_fmac_f32_dpp v143, v77, v145 row_shr:1 row_mask:0xf bank_mask:0xf bound_ctrl:1
	v_fmac_f32_dpp v213, v93, v161 row_shl:1 row_mask:0xf bank_mask:0xf bound_ctrl:1
	v_pk_mul_f32 v[218:219], v[142:143], s[54:55] op_sel_hi:[1,0]
	v_pk_mul_f32 v[252:253], v[178:179], s[54:55] op_sel_hi:[1,0]
	v_pk_mul_f32 v[228:229], v[210:211], s[54:55] op_sel_hi:[1,0]
	v_pk_mul_f32 v[230:231], v[212:213], s[54:55] op_sel_hi:[1,0]
	v_exp_f32_e32 v218, v218
	v_exp_f32_e32 v219, v219
	v_exp_f32_e32 v252, v252
	v_exp_f32_e32 v253, v253
	v_exp_f32_e32 v228, v228
	v_exp_f32_e32 v229, v229
	v_exp_f32_e32 v230, v230
	v_exp_f32_e32 v231, v231
	v_pk_add_f32 v[218:219], v[218:219], s[56:57] op_sel_hi:[1,0]
	v_pk_add_f32 v[252:253], v[252:253], s[56:57] op_sel_hi:[1,0]
	v_pk_add_f32 v[228:229], v[228:229], s[56:57] op_sel_hi:[1,0]
	v_pk_add_f32 v[230:231], v[230:231], s[56:57] op_sel_hi:[1,0]
	v_rcp_f32_e32 v218, v218
	v_rcp_f32_e32 v219, v219
	v_rcp_f32_e32 v252, v252
	v_rcp_f32_e32 v253, v253
	v_rcp_f32_e32 v228, v228
	v_rcp_f32_e32 v229, v229
	v_rcp_f32_e32 v230, v230
	v_rcp_f32_e32 v231, v231
	v_pk_mul_f32 v[142:143], v[142:143], v[218:219]
	v_pk_mul_f32 v[178:179], v[178:179], v[252:253]
	v_pk_mul_f32 v[210:211], v[210:211], v[228:229]
	v_pk_mul_f32 v[212:213], v[212:213], v[230:231]
	v_pk_fma_f32 v[218:219], v[188:189], v[84:85], v[220:221]
	v_pk_fma_f32 v[252:253], v[188:189], v[28:29], v[220:221]
	v_pk_fma_f32 v[228:229], v[188:189], v[24:25], v[220:221]
	v_pk_fma_f32 v[230:231], v[188:189], v[72:73], v[220:221]
	v_pk_fma_f32 v[218:219], v[200:201], v[28:29], v[218:219]
	v_pk_fma_f32 v[252:253], v[180:181], v[84:85], v[252:253]
	v_pk_fma_f32 v[228:229], v[180:181], v[28:29], v[228:229]
	v_pk_fma_f32 v[230:231], v[180:181], v[24:25], v[230:231]
	v_pk_fma_f32 v[252:253], v[200:201], v[24:25], v[252:253]
	v_pk_fma_f32 v[228:229], v[200:201], v[72:73], v[228:229]
	v_fmac_f32_dpp v218, v72, v180 row_shr:1 row_mask:0xf bank_mask:0xf bound_ctrl:1
	v_fmac_f32_dpp v230, v84, v200 row_shl:1 row_mask:0xf bank_mask:0xf bound_ctrl:1
	v_fmac_f32_dpp v219, v73, v181 row_shr:1 row_mask:0xf bank_mask:0xf bound_ctrl:1
	v_fmac_f32_dpp v231, v85, v201 row_shl:1 row_mask:0xf bank_mask:0xf bound_ctrl:1
	v_pk_mul_f32 v[142:143], v[142:143], v[218:219]
	v_pk_mul_f32 v[178:179], v[178:179], v[252:253]
	v_pk_mul_f32 v[210:211], v[210:211], v[228:229]
	v_pk_mul_f32 v[212:213], v[212:213], v[230:231]
	v_cvt_pk_bf16_f32 v236, v142, v143
; __device__ __forceinline__ unsigned cvt_pk_bf16(float lo, float hi) { unsigned r; asm volatile("v_cvt_pk_bf16_f32 %0, %1, %2" : "=v"(r) : "v"(lo), "v"(hi)); return r; }
; template <int CTRL> __device__ __forceinline__ float dppz(float v) { return __int_as_float(__builtin_amdgcn_update_dpp(0, __float_as_int(v), CTRL, 0xf, 0xf, true)); }
;     __device__ __forceinline__ void operator()(f32x4 (&acc)[2][2][4][2], const Unit& u, int wr, int wc, int fr, int fq, const LAS float* rtab) const {
;     ...
;                         const float gc = acc[ai][0][m][n][jj], uc = acc[ai][1][m][n][jj];
;                         const float gb = m > 0 ? acc[ai][0][m - 1][n][jj] : 0.f, ga = m < 3 ? acc[ai][0][m + 1][n][jj] : 0.f;
;                         const float ub = m > 0 ? acc[ai][1][m - 1][n][jj] : 0.f, ua = m < 3 ? acc[ai][1][m + 1][n][jj] : 0.f;
;                         const float gp = dppz<0x111>(gc) + dppz<0x10F>(gb), gn = dppz<0x101>(gc) + dppz<0x11F>(ga);
;                         const float up = dppz<0x111>(uc) + dppz<0x10F>(ub), un = dppz<0x101>(uc) + dppz<0x11F>(ua);
;                         const float hg = wg0[jj] * gp + wg1[jj] * gc + wg2[jj] * gn + bg[jj];
;                         const float hu = wu0[jj] * up + wu1[jj] * uc + wu2[jj] * un + bu[jj];
;                         const float sg = __builtin_amdgcn_rcpf(1.f + __builtin_amdgcn_exp2f(-1.4426950408889634f * hg));
;                         y[jj] = hg * sg * hu; }
;                     u32x2 pk; pk.x = cvt_pk_bf16(y[0], y[1]); pk.y = cvt_pk_bf16(y[2], y[3]);
	v_cvt_pk_bf16_f32 v240, v178, v179
	v_cvt_pk_bf16_f32 v244, v210, v211
	v_cvt_pk_bf16_f32 v248, v212, v213
	v_pk_fma_f32 v[142:143], v[154:155], v[94:95], v[170:171]
	v_pk_fma_f32 v[178:179], v[154:155], v[38:39], v[170:171]
	v_pk_fma_f32 v[210:211], v[154:155], v[34:35], v[170:171]
	v_pk_fma_f32 v[212:213], v[154:155], v[78:79], v[170:171]
	v_pk_fma_f32 v[142:143], v[162:163], v[38:39], v[142:143]
	v_pk_fma_f32 v[178:179], v[146:147], v[94:95], v[178:179]
	v_pk_fma_f32 v[210:211], v[146:147], v[38:39], v[210:211]
	v_pk_fma_f32 v[212:213], v[146:147], v[34:35], v[212:213]
	v_pk_fma_f32 v[178:179], v[162:163], v[34:35], v[178:179]
	v_pk_fma_f32 v[210:211], v[162:163], v[78:79], v[210:211]
	v_fmac_f32_dpp v142, v78, v146 row_shr:1 row_mask:0xf bank_mask:0xf bound_ctrl:1
	v_fmac_f32_dpp v212, v94, v162 row_shl:1 row_mask:0xf bank_mask:0xf bound_ctrl:1
	v_fmac_f32_dpp v143, v79, v147 row_shr:1 row_mask:0xf bank_mask:0xf bound_ctrl:1
	v_fmac_f32_dpp v213, v95, v163 row_shl:1 row_mask:0xf bank_mask:0xf bound_ctrl:1
	v_pk_mul_f32 v[218:219], v[142:143], s[54:55] op_sel_hi:[1,0]
	v_pk_mul_f32 v[252:253], v[178:179], s[54:55] op_sel_hi:[1,0]
	v_pk_mul_f32 v[228:229], v[210:211], s[54:55] op_sel_hi:[1,0]
	v_pk_mul_f32 v[230:231], v[212:213], s[54:55] op_sel_hi:[1,0]
	v_exp_f32_e32 v218, v218
	v_exp_f32_e32 v219, v219
	v_exp_f32_e32 v252, v252
	v_exp_f32_e32 v253, v253
	v_exp_f32_e32 v228, v228
	v_exp_f32_e32 v229, v229
	v_exp_f32_e32 v230, v230
	v_exp_f32_e32 v231, v231
	v_pk_add_f32 v[218:219], v[218:219], s[56:57] op_sel_hi:[1,0]
	v_pk_add_f32 v[252:253], v[252:253], s[56:57] op_sel_hi:[1,0]
	v_pk_add_f32 v[228:229], v[228:229], s[56:57] op_sel_hi:[1,0]
	v_pk_add_f32 v[230:231], v[230:231], s[56:57] op_sel_hi:[1,0]
	v_rcp_f32_e32 v218, v218
	v_rcp_f32_e32 v219, v219
	v_rcp_f32_e32 v252, v252
	v_rcp_f32_e32 v253, v253
	v_rcp_f32_e32 v228, v228
	v_rcp_f32_e32 v229, v229
	v_rcp_f32_e32 v230, v230
	v_rcp_f32_e32 v231, v231
	v_pk_mul_f32 v[142:143], v[142:143], v[218:219]
	v_pk_mul_f32 v[178:179], v[178:179], v[252:253]
	v_pk_mul_f32 v[210:211], v[210:211], v[228:229]
	v_pk_mul_f32 v[212:213], v[212:213], v[230:231]
	v_pk_fma_f32 v[218:219], v[190:191], v[86:87], v[222:223]
	v_pk_fma_f32 v[252:253], v[190:191], v[30:31], v[222:223]
	v_pk_fma_f32 v[228:229], v[190:191], v[26:27], v[222:223]
	v_pk_fma_f32 v[230:231], v[190:191], v[74:75], v[222:223]
	v_pk_fma_f32 v[218:219], v[202:203], v[30:31], v[218:219]
	v_pk_fma_f32 v[252:253], v[182:183], v[86:87], v[252:253]
	v_pk_fma_f32 v[228:229], v[182:183], v[30:31], v[228:229]
	v_pk_fma_f32 v[230:231], v[182:183], v[26:27], v[230:231]
	v_pk_fma_f32 v[252:253], v[202:203], v[26:27], v[252:253]
	v_pk_fma_f32 v[228:229], v[202:203], v[74:75], v[228:229]
	v_fmac_f32_dpp v218, v74, v182 row_shr:1 row_mask:0xf bank_mask:0xf bound_ctrl:1
	v_fmac_f32_dpp v230, v86, v202 row_shl:1 row_mask:0xf bank_mask:0xf bound_ctrl:1
	v_fmac_f32_dpp v219, v75, v183 row_shr:1 row_mask:0xf bank_mask:0xf bound_ctrl:1
	v_fmac_f32_dpp v231, v87, v203 row_shl:1 row_mask:0xf bank_mask:0xf bound_ctrl:1
	v_pk_mul_f32 v[142:143], v[142:143], v[218:219]
	v_pk_mul_f32 v[178:179], v[178:179], v[252:253]
	v_pk_mul_f32 v[210:211], v[210:211], v[228:229]
	v_pk_mul_f32 v[212:213], v[212:213], v[230:231]
	v_cvt_pk_bf16_f32 v237, v142, v143
	v_cvt_pk_bf16_f32 v241, v178, v179
	v_cvt_pk_bf16_f32 v245, v210, v211
	v_cvt_pk_bf16_f32 v249, v212, v213
	v_pk_fma_f32 v[142:143], v[156:157], v[88:89], v[172:173]
	v_pk_fma_f32 v[178:179], v[156:157], v[12:13], v[172:173]
	v_pk_fma_f32 v[210:211], v[156:157], v[4:5], v[172:173]
	v_pk_fma_f32 v[212:213], v[156:157], v[56:57], v[172:173]
	v_pk_fma_f32 v[142:143], v[164:165], v[12:13], v[142:143]
	v_pk_fma_f32 v[178:179], v[148:149], v[88:89], v[178:179]
	v_pk_fma_f32 v[210:211], v[148:149], v[12:13], v[210:211]
	v_pk_fma_f32 v[212:213], v[148:149], v[4:5], v[212:213]
	v_pk_fma_f32 v[178:179], v[164:165], v[4:5], v[178:179]
	v_pk_fma_f32 v[210:211], v[164:165], v[56:57], v[210:211]
	v_fmac_f32_dpp v142, v56, v148 row_shr:1 row_mask:0xf bank_mask:0xf bound_ctrl:1
	v_fmac_f32_dpp v212, v88, v164 row_shl:1 row_mask:0xf bank_mask:0xf bound_ctrl:1
	v_fmac_f32_dpp v143, v57, v149 row_shr:1 row_mask:0xf bank_mask:0xf bound_ctrl:1
	v_fmac_f32_dpp v213, v89, v165 row_shl:1 row_mask:0xf bank_mask:0xf bound_ctrl:1
	v_pk_mul_f32 v[218:219], v[142:143], s[54:55] op_sel_hi:[1,0]
	v_pk_mul_f32 v[252:253], v[178:179], s[54:55] op_sel_hi:[1,0]
	v_pk_mul_f32 v[228:229], v[210:211], s[54:55] op_sel_hi:[1,0]
	v_pk_mul_f32 v[230:231], v[212:213], s[54:55] op_sel_hi:[1,0]
	v_exp_f32_e32 v218, v218
	v_exp_f32_e32 v219, v219
	v_exp_f32_e32 v252, v252
	v_exp_f32_e32 v253, v253
	v_exp_f32_e32 v228, v228
	v_exp_f32_e32 v229, v229
	v_exp_f32_e32 v230, v230
	v_exp_f32_e32 v231, v231
	v_pk_add_f32 v[218:219], v[218:219], s[56:57] op_sel_hi:[1,0]
	v_pk_add_f32 v[252:253], v[252:253], s[56:57] op_sel_hi:[1,0]
	v_pk_add_f32 v[228:229], v[228:229], s[56:57] op_sel_hi:[1,0]
	v_pk_add_f32 v[230:231], v[230:231], s[56:57] op_sel_hi:[1,0]
	v_rcp_f32_e32 v218, v218
	v_rcp_f32_e32 v219, v219
	v_rcp_f32_e32 v252, v252
	v_rcp_f32_e32 v253, v253
	v_rcp_f32_e32 v228, v228
	v_rcp_f32_e32 v229, v229
	v_rcp_f32_e32 v230, v230
	v_rcp_f32_e32 v231, v231
	v_pk_mul_f32 v[142:143], v[142:143], v[218:219]
; __device__ __forceinline__ unsigned cvt_pk_bf16(float lo, float hi) { unsigned r; asm volatile("v_cvt_pk_bf16_f32 %0, %1, %2" : "=v"(r) : "v"(lo), "v"(hi)); return r; }
; template <int CTRL> __device__ __forceinline__ float dppz(float v) { return __int_as_float(__builtin_amdgcn_update_dpp(0, __float_as_int(v), CTRL, 0xf, 0xf, true)); }
;     __device__ __forceinline__ void operator()(f32x4 (&acc)[2][2][4][2], const Unit& u, int wr, int wc, int fr, int fq, const LAS float* rtab) const {
;     ...
;                         const float gc = acc[ai][0][m][n][jj], uc = acc[ai][1][m][n][jj];
;                         const float gb = m > 0 ? acc[ai][0][m - 1][n][jj] : 0.f, ga = m < 3 ? acc[ai][0][m + 1][n][jj] : 0.f;
;                         const float ub = m > 0 ? acc[ai][1][m - 1][n][jj] : 0.f, ua = m < 3 ? acc[ai][1][m + 1][n][jj] : 0.f;
;                         const float gp = dppz<0x111>(gc) + dppz<0x10F>(gb), gn = dppz<0x101>(gc) + dppz<0x11F>(ga);
;                         const float up = dppz<0x111>(uc) + dppz<0x10F>(ub), un = dppz<0x101>(uc) + dppz<0x11F>(ua);
;                         const float hg = wg0[jj] * gp + wg1[jj] * gc + wg2[jj] * gn + bg[jj];
;                         const float hu = wu0[jj] * up + wu1[jj] * uc + wu2[jj] * un + bu[jj];
;                         const float sg = __builtin_amdgcn_rcpf(1.f + __builtin_amdgcn_exp2f(-1.4426950408889634f * hg));
;                         y[jj] = hg * sg * hu; }
;                     u32x2 pk; pk.x = cvt_pk_bf16(y[0], y[1]); pk.y = cvt_pk_bf16(y[2], y[3]);
;                     if (n == 0) ypk[ai][m] = pk;
;                     else {
;                         const bool deferred = (m == 0 && fr == 0) || (m == 3 && fr == 15);
;                         if (!deferred) { u32x4 w; w.x = ypk[ai][m].x; w.y = ypk[ai][m].y; w.z = pk.x; w.w = pk.y; *(u32x4*)(act + (size_t)(r64 + m * 16 + fr) * DFF + c0) = w; } }
	v_pk_mul_f32 v[178:179], v[178:179], v[252:253]
	v_pk_mul_f32 v[210:211], v[210:211], v[228:229]
	v_pk_mul_f32 v[212:213], v[212:213], v[230:231]
	v_pk_fma_f32 v[218:219], v[196:197], v[80:81], v[224:225]
	v_pk_fma_f32 v[252:253], v[196:197], v[8:9], v[224:225]
	v_pk_fma_f32 v[228:229], v[196:197], v[0:1], v[224:225]
	v_pk_fma_f32 v[230:231], v[196:197], v[40:41], v[224:225]
	v_pk_fma_f32 v[218:219], v[204:205], v[8:9], v[218:219]
	v_pk_fma_f32 v[252:253], v[184:185], v[80:81], v[252:253]
	v_pk_fma_f32 v[228:229], v[184:185], v[8:9], v[228:229]
	v_pk_fma_f32 v[230:231], v[184:185], v[0:1], v[230:231]
	v_pk_fma_f32 v[252:253], v[204:205], v[0:1], v[252:253]
	v_pk_fma_f32 v[228:229], v[204:205], v[40:41], v[228:229]
	v_fmac_f32_dpp v218, v40, v184 row_shr:1 row_mask:0xf bank_mask:0xf bound_ctrl:1
	v_fmac_f32_dpp v230, v80, v204 row_shl:1 row_mask:0xf bank_mask:0xf bound_ctrl:1
	v_fmac_f32_dpp v219, v41, v185 row_shr:1 row_mask:0xf bank_mask:0xf bound_ctrl:1
	v_fmac_f32_dpp v231, v81, v205 row_shl:1 row_mask:0xf bank_mask:0xf bound_ctrl:1
	v_pk_mul_f32 v[142:143], v[142:143], v[218:219]
	v_pk_mul_f32 v[178:179], v[178:179], v[252:253]
	v_pk_mul_f32 v[210:211], v[210:211], v[228:229]
	v_pk_mul_f32 v[212:213], v[212:213], v[230:231]
	v_cvt_pk_bf16_f32 v238, v142, v143
	v_cvt_pk_bf16_f32 v242, v178, v179
	v_cvt_pk_bf16_f32 v246, v210, v211
	v_cvt_pk_bf16_f32 v250, v212, v213
	v_pk_fma_f32 v[142:143], v[158:159], v[90:91], v[174:175]
	v_pk_fma_f32 v[178:179], v[158:159], v[14:15], v[174:175]
	v_pk_fma_f32 v[210:211], v[158:159], v[6:7], v[174:175]
	v_pk_fma_f32 v[212:213], v[158:159], v[58:59], v[174:175]
	v_pk_fma_f32 v[142:143], v[166:167], v[14:15], v[142:143]
	v_pk_fma_f32 v[178:179], v[150:151], v[90:91], v[178:179]
	v_pk_fma_f32 v[210:211], v[150:151], v[14:15], v[210:211]
	v_pk_fma_f32 v[212:213], v[150:151], v[6:7], v[212:213]
	v_pk_fma_f32 v[178:179], v[166:167], v[6:7], v[178:179]
	v_pk_fma_f32 v[210:211], v[166:167], v[58:59], v[210:211]
	v_fmac_f32_dpp v142, v58, v150 row_shr:1 row_mask:0xf bank_mask:0xf bound_ctrl:1
	v_fmac_f32_dpp v212, v90, v166 row_shl:1 row_mask:0xf bank_mask:0xf bound_ctrl:1
	v_fmac_f32_dpp v143, v59, v151 row_shr:1 row_mask:0xf bank_mask:0xf bound_ctrl:1
	v_fmac_f32_dpp v213, v91, v167 row_shl:1 row_mask:0xf bank_mask:0xf bound_ctrl:1
	v_pk_mul_f32 v[218:219], v[142:143], s[54:55] op_sel_hi:[1,0]
	v_pk_mul_f32 v[252:253], v[178:179], s[54:55] op_sel_hi:[1,0]
	v_pk_mul_f32 v[228:229], v[210:211], s[54:55] op_sel_hi:[1,0]
	v_pk_mul_f32 v[230:231], v[212:213], s[54:55] op_sel_hi:[1,0]
	v_exp_f32_e32 v218, v218
	v_exp_f32_e32 v219, v219
	v_exp_f32_e32 v252, v252
	v_exp_f32_e32 v253, v253
	v_exp_f32_e32 v228, v228
	v_exp_f32_e32 v229, v229
	v_exp_f32_e32 v230, v230
	v_exp_f32_e32 v231, v231
	v_pk_add_f32 v[218:219], v[218:219], s[56:57] op_sel_hi:[1,0]
	v_pk_add_f32 v[252:253], v[252:253], s[56:57] op_sel_hi:[1,0]
	v_pk_add_f32 v[228:229], v[228:229], s[56:57] op_sel_hi:[1,0]
	v_pk_add_f32 v[230:231], v[230:231], s[56:57] op_sel_hi:[1,0]
	v_rcp_f32_e32 v218, v218
	v_rcp_f32_e32 v219, v219
	v_rcp_f32_e32 v252, v252
	v_rcp_f32_e32 v253, v253
	v_rcp_f32_e32 v228, v228
	v_rcp_f32_e32 v229, v229
	v_rcp_f32_e32 v230, v230
	v_rcp_f32_e32 v231, v231
	v_pk_mul_f32 v[142:143], v[142:143], v[218:219]
	v_pk_mul_f32 v[178:179], v[178:179], v[252:253]
	v_pk_mul_f32 v[210:211], v[210:211], v[228:229]
	v_pk_mul_f32 v[212:213], v[212:213], v[230:231]
	v_pk_fma_f32 v[218:219], v[198:199], v[82:83], v[226:227]
	v_pk_fma_f32 v[252:253], v[198:199], v[10:11], v[226:227]
	v_pk_fma_f32 v[228:229], v[198:199], v[2:3], v[226:227]
	v_pk_fma_f32 v[230:231], v[198:199], v[42:43], v[226:227]
	v_pk_fma_f32 v[218:219], v[206:207], v[10:11], v[218:219]
	v_pk_fma_f32 v[252:253], v[186:187], v[82:83], v[252:253]
	v_pk_fma_f32 v[228:229], v[186:187], v[10:11], v[228:229]
	v_pk_fma_f32 v[230:231], v[186:187], v[2:3], v[230:231]
	v_pk_fma_f32 v[252:253], v[206:207], v[2:3], v[252:253]
	v_pk_fma_f32 v[228:229], v[206:207], v[42:43], v[228:229]
	v_fmac_f32_dpp v218, v42, v186 row_shr:1 row_mask:0xf bank_mask:0xf bound_ctrl:1
	v_fmac_f32_dpp v230, v82, v206 row_shl:1 row_mask:0xf bank_mask:0xf bound_ctrl:1
	v_fmac_f32_dpp v219, v43, v187 row_shr:1 row_mask:0xf bank_mask:0xf bound_ctrl:1
	v_fmac_f32_dpp v231, v83, v207 row_shl:1 row_mask:0xf bank_mask:0xf bound_ctrl:1
	v_pk_mul_f32 v[142:143], v[142:143], v[218:219]
	v_pk_mul_f32 v[178:179], v[178:179], v[252:253]
	v_pk_mul_f32 v[210:211], v[210:211], v[228:229]
	v_pk_mul_f32 v[212:213], v[212:213], v[230:231]
	v_cvt_pk_bf16_f32 v239, v142, v143
	v_cvt_pk_bf16_f32 v243, v178, v179
	v_cvt_pk_bf16_f32 v247, v210, v211
	v_cvt_pk_bf16_f32 v251, v212, v213
	s_add_u32 s58, s28, 0x160000
	s_addc_u32 s59, s29, 0
	s_mov_b64 exec, s[12:13]
	global_store_dwordx4 v234, v[236:239], s[58:59]
	s_mov_b64 exec, -1
	s_add_u32 s58, s28, 0x162c00
	s_addc_u32 s59, s29, 0
	global_store_dwordx4 v234, v[240:243], s[58:59]
	s_add_u32 s58, s28, 0x165800
	s_addc_u32 s59, s29, 0
	global_store_dwordx4 v234, v[244:247], s[58:59]
	s_add_u32 s58, s28, 0x168400
	s_addc_u32 s59, s29, 0
	s_mov_b64 exec, s[10:11]
	global_store_dwordx4 v234, v[248:251], s[58:59]
	s_mov_b64 exec, -1
	s_andn2_b64 vcc, exec, s[52:53]
	s_mov_b64 s[52:53], -1
	s_cbranch_vccnz .LBB0_834
